# k9 with static priority for waves 0-3 (the other half) at each GEMM phase start, per-segment flips deleted
# speedup vs baseline: 1.0078x; 1.0078x over previous
;     __device__ __forceinline__ unsigned char* ws() const { return (unsigned char*)(__attribute__((address_space(1))) unsigned char*)get(21); }
; #define GBAR() do { XcdBarrier xb_; xb_.bar = (unsigned*)(A.ws() + WS_CTL); xb_.x = xb_xcc_id(); { unsigned a_; asm volatile("v_mov_b32 %0, %1" : "=v"(a_) : "s"(A.base + 192u)); xb_.st = (volatile LAS unsigned*)a_; } xcd_barrier(xb_, wv0); } while (0)
; #define FRESH() do { ws = opaque_p(A.ws()); tid = opaque(TID()); lane = tid & 63; wave = __builtin_amdgcn_readfirstlane(tid >> 6); G = opaque_s(gridDim.x); c = opaque_s(blockIdx.x); gw = c * 8 + wave; NGW = G * 8; } while (0)
; template <int l>
; __device__ __forceinline__ void layer_body(const Ptrs& A, LAS unsigned char* lds, unsigned char* lds_raw, const int wv0) {
;     ...
;         if constexpr (l == 0) cg::this_grid().sync(); else GBAR();
;         if (DUP_SYNC) { GBAR(); GBAR(); }
;         FRESH();
;         if (PH(2)) {
;             pg8::Gemm g{DM, DM, DM}; pg8::SchedGrid S; S.to.init(T / 256, NP / 256); S.G = G; S.c = c; S.A = (const char*)(ws + WS_H); S.B = (const char*)(ws + WS_WIN); S.ta = (size_t)256 * DM * 2; S.tb = (size_t)256 * DM * 2;
;             pg8::EpiProj E{ws};
; #pragma unroll 1
;             for (int rep = 0; rep < 1 + DUP_GEMM; ++rep) { pg8::gemm_phase<pg8::EpiProj, pg8::SchedGrid, true, true>(lds, g, S, E, wv0); __syncthreads(); }
.LBB0_73:
	s_or_b64 exec, exec, s[0:1]
	s_barrier
	v_readfirstlane_b32 s79, v204
	s_lshr_b32 s79, s79, 6
	s_cmp_lt_u32 s79, 4
	s_cbranch_scc0 .Lprio_skip_9
	s_setprio 1

;     __device__ __forceinline__ unsigned char* ws() const { return (unsigned char*)(__attribute__((address_space(1))) unsigned char*)get(21); }
; #define GBAR() do { XcdBarrier xb_; xb_.bar = (unsigned*)(A.ws() + WS_CTL); xb_.x = xb_xcc_id(); { unsigned a_; asm volatile("v_mov_b32 %0, %1" : "=v"(a_) : "s"(A.base + 192u)); xb_.st = (volatile LAS unsigned*)a_; } xcd_barrier(xb_, wv0); } while (0)
; #define FRESH() do { ws = opaque_p(A.ws()); tid = opaque(TID()); lane = tid & 63; wave = __builtin_amdgcn_readfirstlane(tid >> 6); G = opaque_s(gridDim.x); c = opaque_s(blockIdx.x); gw = c * 8 + wave; NGW = G * 8; } while (0)
; template <int l>
; __device__ __forceinline__ void layer_body(const Ptrs& A, LAS unsigned char* lds, unsigned char* lds_raw, const int wv0) {
;     ...
;         GBAR();
;         if (DUP_SYNC) { GBAR(); GBAR(); }
;         FRESH();
;         if (PH(6)) {
;             pg8::Gemm g{1024, 1024, 1024}; pg8::SchedBranch S; S.to.init(T / 256, DM / 256); S.G = G; S.c = c; S.A = (const char*)(ws + WS_ABR); S.B = (const char*)(ws + WS_WBR);
;             pg8::EpiMerge E{(const unsigned char*)(ws + WS_GATES), (bf16*)(ws + WS_GV)};
; #pragma unroll 1
;             for (int rep = 0; rep < 1 + DUP_GEMM; ++rep) { pg8::gemm_phase<pg8::EpiMerge, pg8::SchedBranch, true, true>(lds, g, S, E, wv0); __syncthreads(); }
.LBB0_479:
	s_or_b64 exec, exec, s[0:1]
	s_waitcnt lgkmcnt(0)
	s_barrier
	v_readfirstlane_b32 s79, v204
	s_lshr_b32 s79, s79, 6
	s_cmp_lt_u32 s79, 4
	s_cbranch_scc0 .Lprio_skip_8
	s_setprio 1
